# v46 + windowed attention: loop-carried state kept in place (P.V MFMAs accumulate into the o registers, in-place rescale); ~50 v_mov_b64 phi copies per tile step removed
# baseline (speedup 1.0000x reference)
.LBB0_1347:
	s_xor_b32 s96, s96, 1
	s_add_u32 s78, s78, 0x4000
	s_addc_u32 s79, s79, 0
	s_add_u32 s80, s80, 0x4000
	s_addc_u32 s81, s81, 0
	v_subrev_u32_e32 v183, 64, v183
	s_add_i32 s0, s0, 64
	s_and_b64 vcc, exec, s[82:83]
	s_cbranch_vccnz .Lswa_exit
	s_mov_b32 s82, s67
	v_mov_b32_e32 v185, v98
	s_branch .LBB0_1343
.Lswa_exit:
	s_nop 3
	v_mov_b64_e32 v[64:65], v[32:33]
	v_mov_b64_e32 v[62:63], v[30:31]
	v_mov_b64_e32 v[60:61], v[28:29]
	v_mov_b64_e32 v[58:59], v[26:27]
	v_mov_b64_e32 v[56:57], v[24:25]
	v_mov_b64_e32 v[54:55], v[22:23]
	v_mov_b64_e32 v[52:53], v[20:21]
	v_mov_b64_e32 v[50:51], v[18:19]
	v_mov_b64_e32 v[48:49], v[16:17]
	v_mov_b64_e32 v[46:47], v[14:15]
	v_mov_b64_e32 v[44:45], v[12:13]
	v_mov_b64_e32 v[42:43], v[10:11]
	v_mov_b64_e32 v[40:41], v[8:9]
	v_mov_b64_e32 v[38:39], v[6:7]
	v_mov_b64_e32 v[36:37], v[4:5]
	v_mov_b64_e32 v[34:35], v[2:3]
	s_branch .LBB0_1403

.LBB0_1364:
	v_max_f32_e32 v34, v99, v99
	v_max_f32_e32 v35, v98, v98
	v_max_f32_e32 v34, v35, v34
	v_max3_f32 v35, v100, v101, v115
	v_max3_f32 v34, v34, v114, v116
	v_max3_f32 v34, v34, v117, v102
	v_max3_f32 v35, v35, v104, v105
	v_max3_f32 v34, v34, v103, v118
	v_max3_f32 v35, v35, v120, v121
	v_max3_f32 v34, v34, v119, v106
	v_max3_f32 v35, v35, v108, v109
	v_max3_f32 v34, v34, v107, v122
	v_max3_f32 v35, v35, v124, v125
	v_max3_f32 v34, v34, v123, v110
	v_max3_f32 v35, v35, v112, v113
	v_max3_f32 v34, v34, v111, v126
	v_max3_f32 v35, v35, v128, v129
	v_max3_f32 v34, v34, v127, v35
	v_mov_b32_e32 v35, v34
	s_nop 1
	v_permlane32_swap_b32_e32 v34, v35
	v_max_f32_e32 v35, v35, v35
	v_max_f32_e32 v34, v34, v34
	v_max_f32_e32 v215, v34, v35
	v_cmp_lt_f32_e32 vcc, s36, v215
	s_cbranch_vccz .LBB0_1368
	v_max_f32_e32 v34, v215, v215
	v_max_f32_e32 v34, 0, v34
	v_exp_f32_e64 v35, -v34
	v_add_f32_e32 v187, v187, v34
	v_xor_b32_e32 v66, 0x80000000, v187
	v_mov_b32_e32 v67, v66
	v_mov_b32_e32 v68, v66
	v_mov_b32_e32 v69, v66
	v_mov_b32_e32 v70, v66
	v_mov_b32_e32 v71, v66
	v_mov_b32_e32 v72, v66
	v_mov_b32_e32 v73, v66
	v_mov_b32_e32 v74, v66
	v_mov_b32_e32 v75, v66
	v_mov_b32_e32 v76, v66
	v_mov_b32_e32 v77, v66
	v_mov_b32_e32 v78, v66
	v_mov_b32_e32 v79, v66
	v_mov_b32_e32 v80, v66
	v_mov_b32_e32 v81, v66
	s_and_saveexec_b64 s[88:89], s[6:7]
	ds_write_b32 v202, v35 offset:40960
	s_or_b64 exec, exec, s[88:89]
	ds_read_b128 v[38:41], v204 offset:41024
	ds_read_b128 v[42:45], v204 offset:41056
	ds_read_b128 v[216:219], v204 offset:40960
	ds_read_b128 v[220:223], v204 offset:40992
	v_pk_add_f32 v[98:99], v[98:99], v[34:35] op_sel_hi:[1,0] neg_lo:[0,1] neg_hi:[0,1]
	v_pk_add_f32 v[114:115], v[114:115], v[34:35] op_sel_hi:[1,0] neg_lo:[0,1] neg_hi:[0,1]
	v_pk_add_f32 v[100:101], v[100:101], v[34:35] op_sel_hi:[1,0] neg_lo:[0,1] neg_hi:[0,1]
	v_pk_add_f32 v[116:117], v[116:117], v[34:35] op_sel_hi:[1,0] neg_lo:[0,1] neg_hi:[0,1]
	v_pk_add_f32 v[102:103], v[102:103], v[34:35] op_sel_hi:[1,0] neg_lo:[0,1] neg_hi:[0,1]
	v_pk_add_f32 v[118:119], v[118:119], v[34:35] op_sel_hi:[1,0] neg_lo:[0,1] neg_hi:[0,1]
	v_pk_add_f32 v[104:105], v[104:105], v[34:35] op_sel_hi:[1,0] neg_lo:[0,1] neg_hi:[0,1]
	v_pk_add_f32 v[120:121], v[120:121], v[34:35] op_sel_hi:[1,0] neg_lo:[0,1] neg_hi:[0,1]
	v_pk_add_f32 v[106:107], v[106:107], v[34:35] op_sel_hi:[1,0] neg_lo:[0,1] neg_hi:[0,1]
	v_pk_add_f32 v[122:123], v[122:123], v[34:35] op_sel_hi:[1,0] neg_lo:[0,1] neg_hi:[0,1]
	v_pk_add_f32 v[108:109], v[108:109], v[34:35] op_sel_hi:[1,0] neg_lo:[0,1] neg_hi:[0,1]
	v_pk_add_f32 v[124:125], v[124:125], v[34:35] op_sel_hi:[1,0] neg_lo:[0,1] neg_hi:[0,1]
	v_pk_add_f32 v[110:111], v[110:111], v[34:35] op_sel_hi:[1,0] neg_lo:[0,1] neg_hi:[0,1]
	v_pk_add_f32 v[126:127], v[126:127], v[34:35] op_sel_hi:[1,0] neg_lo:[0,1] neg_hi:[0,1]
	v_pk_add_f32 v[112:113], v[112:113], v[34:35] op_sel_hi:[1,0] neg_lo:[0,1] neg_hi:[0,1]
	v_pk_add_f32 v[128:129], v[128:129], v[34:35] op_sel_hi:[1,0] neg_lo:[0,1] neg_hi:[0,1]
	v_mul_f32_e32 v185, v185, v35
	s_waitcnt lgkmcnt(2)
	v_pk_mul_f32 v[32:33], v[32:33], v[44:45]
	v_pk_mul_f32 v[28:29], v[28:29], v[40:41]
	s_waitcnt lgkmcnt(0)
	v_pk_mul_f32 v[24:25], v[24:25], v[222:223]
	v_pk_mul_f32 v[20:21], v[20:21], v[218:219]
	v_pk_mul_f32 v[16:17], v[16:17], v[44:45]
	v_pk_mul_f32 v[12:13], v[12:13], v[40:41]
	v_pk_mul_f32 v[8:9], v[8:9], v[222:223]
	v_pk_mul_f32 v[4:5], v[4:5], v[218:219]
	v_pk_mul_f32 v[30:31], v[30:31], v[42:43]
	v_pk_mul_f32 v[26:27], v[26:27], v[38:39]
	v_pk_mul_f32 v[22:23], v[22:23], v[220:221]
	v_pk_mul_f32 v[18:19], v[18:19], v[216:217]
	v_pk_mul_f32 v[14:15], v[14:15], v[42:43]
	v_pk_mul_f32 v[10:11], v[10:11], v[38:39]
	v_pk_mul_f32 v[6:7], v[6:7], v[220:221]
	v_pk_mul_f32 v[2:3], v[2:3], v[216:217]
.LBB0_1368:
	v_exp_f32_e32 v98, v98
	v_exp_f32_e32 v99, v99
	v_exp_f32_e32 v100, v100
	v_exp_f32_e32 v101, v101
	v_exp_f32_e32 v102, v102
	v_add_f32_e32 v215, v98, v99
	v_exp_f32_e32 v103, v103
	v_add_f32_e32 v215, v100, v215
	v_exp_f32_e32 v104, v104
	v_add_f32_e32 v215, v101, v215
	v_exp_f32_e32 v105, v105
	v_add_f32_e32 v215, v102, v215
	v_exp_f32_e32 v106, v106
	v_add_f32_e32 v215, v103, v215
	v_exp_f32_e32 v107, v107
	v_add_f32_e32 v215, v104, v215
	v_exp_f32_e32 v108, v108
	v_add_f32_e32 v215, v105, v215
	v_exp_f32_e32 v109, v109
	v_add_f32_e32 v215, v106, v215
	v_exp_f32_e32 v110, v110
	v_add_f32_e32 v215, v107, v215
	v_exp_f32_e32 v111, v111
	v_add_f32_e32 v215, v108, v215
	v_exp_f32_e32 v114, v114
	v_add_f32_e32 v215, v109, v215
	v_exp_f32_e32 v115, v115
	v_exp_f32_e32 v112, v112
	v_exp_f32_e32 v116, v116
	v_add_f32_e32 v215, v110, v215
	v_cvt_pk_bf16_f32 v98, v98, v99
	v_cvt_pk_bf16_f32 v99, v100, v101
	v_cvt_pk_bf16_f32 v100, v102, v103
	v_cvt_pk_bf16_f32 v102, v106, v107
	v_add_f32_e32 v106, v111, v215
	v_exp_f32_e32 v117, v117
	v_cvt_pk_bf16_f32 v101, v104, v105
	v_cvt_pk_bf16_f32 v104, v110, v111
	v_add_f32_e32 v110, v112, v106
	v_cvt_pk_bf16_f32 v106, v114, v115
	v_add_f32_e32 v114, v114, v115
	v_exp_f32_e32 v118, v118
	v_add_f32_e32 v114, v116, v114
	v_exp_f32_e32 v119, v119
	v_add_f32_e32 v114, v117, v114
	v_exp_f32_e32 v120, v120
	v_exp_f32_e32 v113, v113
	v_add_f32_e32 v114, v118, v114
	v_exp_f32_e32 v121, v121
	v_mfma_f32_32x32x16_bf16 v[2:17], v[98:101], v[174:177], v[2:17]
	v_exp_f32_e32 v122, v122
	v_add_f32_e32 v114, v119, v114
	v_cvt_pk_bf16_f32 v103, v108, v109
	v_cvt_pk_bf16_f32 v105, v112, v113
	v_add_f32_e32 v114, v120, v114
	s_waitcnt lgkmcnt(6)
	v_mfma_f32_32x32x16_bf16 v[18:33], v[98:101], v[158:161], v[18:33]
	v_exp_f32_e32 v123, v123
	v_exp_f32_e32 v124, v124
	v_add_f32_e32 v98, v121, v114
	v_exp_f32_e32 v125, v125
	v_add_f32_e32 v98, v122, v98
	v_mfma_f32_32x32x16_bf16 v[2:17], v[102:105], v[170:173], v[2:17]
	v_add_f32_e32 v98, v123, v98
	v_exp_f32_e32 v126, v126
	v_add_f32_e32 v98, v124, v98
	v_cvt_pk_bf16_f32 v107, v116, v117
	v_cvt_pk_bf16_f32 v108, v118, v119
	v_cvt_pk_bf16_f32 v109, v120, v121
	s_waitcnt lgkmcnt(4)
	v_mfma_f32_32x32x16_bf16 v[18:33], v[102:105], v[154:157], v[18:33]
	v_exp_f32_e32 v127, v127
	v_add_f32_e32 v98, v125, v98
	v_exp_f32_e32 v128, v128
	v_add_f32_e32 v98, v126, v98
	v_exp_f32_e32 v129, v129
	v_mfma_f32_32x32x16_bf16 v[2:17], v[106:109], v[166:169], v[2:17]
	v_add_f32_e32 v98, v127, v98
	v_cvt_pk_bf16_f32 v111, v124, v125
	v_add_f32_e32 v98, v128, v98
	v_add_f32_e32 v170, v113, v110
	v_cvt_pk_bf16_f32 v110, v122, v123
	s_waitcnt lgkmcnt(2)
	v_mfma_f32_32x32x16_bf16 v[18:33], v[106:109], v[150:153], v[18:33]
	v_cvt_pk_bf16_f32 v112, v126, v127
	v_cvt_pk_bf16_f32 v113, v128, v129
	s_mov_b64 s[88:89], 0
	v_add_f32_e32 v98, v129, v98
	v_mfma_f32_32x32x16_bf16 v[2:17], v[110:113], v[162:165], v[2:17]
	v_add_f32_e32 v98, v170, v98
	s_nop 0
	v_add_f32_e32 v98, v185, v98
	s_waitcnt lgkmcnt(0)
	v_mfma_f32_32x32x16_bf16 v[18:33], v[110:113], v[146:149], v[18:33]

.LBB0_1380:
	s_nop 1
	v_max_f32_e32 v34, v99, v99
	v_max_f32_e32 v35, v98, v98
	v_max_f32_e32 v34, v35, v34
	v_max3_f32 v35, v101, v102, v103
	v_max3_f32 v34, v34, v100, v104
	v_max3_f32 v35, v35, v106, v107
	v_max3_f32 v34, v34, v105, v108
	v_max3_f32 v35, v35, v110, v111
	v_max3_f32 v34, v34, v109, v112
	v_max3_f32 v34, v34, v113, v35
	v_mov_b32_e32 v35, v34
	s_nop 1
	v_permlane32_swap_b32_e32 v34, v35
	v_max_f32_e32 v35, v35, v35
	v_max_f32_e32 v34, v34, v34
	v_max_f32_e32 v147, v34, v35
	v_cmp_lt_f32_e32 vcc, s36, v147
	s_cbranch_vccz .LBB0_1384
	v_max_f32_e32 v34, v147, v147
	v_max_f32_e32 v34, 0, v34
	v_exp_f32_e64 v35, -v34
	v_add_f32_e32 v187, v187, v34
	v_xor_b32_e32 v66, 0x80000000, v187
	v_mov_b32_e32 v67, v66
	v_mov_b32_e32 v68, v66
	v_mov_b32_e32 v69, v66
	v_mov_b32_e32 v70, v66
	v_mov_b32_e32 v71, v66
	v_mov_b32_e32 v72, v66
	v_mov_b32_e32 v73, v66
	v_mov_b32_e32 v74, v66
	v_mov_b32_e32 v75, v66
	v_mov_b32_e32 v76, v66
	v_mov_b32_e32 v77, v66
	v_mov_b32_e32 v78, v66
	v_mov_b32_e32 v79, v66
	v_mov_b32_e32 v80, v66
	v_mov_b32_e32 v81, v66
	s_and_saveexec_b64 s[86:87], s[6:7]
	ds_write_b32 v202, v35 offset:40960
	s_or_b64 exec, exec, s[86:87]
	ds_read_b128 v[38:41], v204 offset:41024
	ds_read_b128 v[42:45], v204 offset:41056
	ds_read_b128 v[148:151], v204 offset:40960
	ds_read_b128 v[152:155], v204 offset:40992
	v_pk_add_f32 v[98:99], v[98:99], v[34:35] op_sel_hi:[1,0] neg_lo:[0,1] neg_hi:[0,1]
	v_pk_add_f32 v[100:101], v[100:101], v[34:35] op_sel_hi:[1,0] neg_lo:[0,1] neg_hi:[0,1]
	v_pk_add_f32 v[102:103], v[102:103], v[34:35] op_sel_hi:[1,0] neg_lo:[0,1] neg_hi:[0,1]
	v_pk_add_f32 v[104:105], v[104:105], v[34:35] op_sel_hi:[1,0] neg_lo:[0,1] neg_hi:[0,1]
	v_pk_add_f32 v[106:107], v[106:107], v[34:35] op_sel_hi:[1,0] neg_lo:[0,1] neg_hi:[0,1]
	v_pk_add_f32 v[108:109], v[108:109], v[34:35] op_sel_hi:[1,0] neg_lo:[0,1] neg_hi:[0,1]
	v_pk_add_f32 v[110:111], v[110:111], v[34:35] op_sel_hi:[1,0] neg_lo:[0,1] neg_hi:[0,1]
	v_pk_add_f32 v[112:113], v[112:113], v[34:35] op_sel_hi:[1,0] neg_lo:[0,1] neg_hi:[0,1]
	v_mul_f32_e32 v185, v185, v35
	s_waitcnt lgkmcnt(2)
	v_pk_mul_f32 v[32:33], v[32:33], v[44:45]
	v_pk_mul_f32 v[28:29], v[28:29], v[40:41]
	s_waitcnt lgkmcnt(0)
	v_pk_mul_f32 v[24:25], v[24:25], v[154:155]
	v_pk_mul_f32 v[20:21], v[20:21], v[150:151]
	v_pk_mul_f32 v[16:17], v[16:17], v[44:45]
	v_pk_mul_f32 v[12:13], v[12:13], v[40:41]
	v_pk_mul_f32 v[8:9], v[8:9], v[154:155]
	v_pk_mul_f32 v[4:5], v[4:5], v[150:151]
	v_pk_mul_f32 v[30:31], v[30:31], v[42:43]
	v_pk_mul_f32 v[26:27], v[26:27], v[38:39]
	v_pk_mul_f32 v[22:23], v[22:23], v[152:153]
	v_pk_mul_f32 v[18:19], v[18:19], v[148:149]
	v_pk_mul_f32 v[14:15], v[14:15], v[42:43]
	v_pk_mul_f32 v[10:11], v[10:11], v[38:39]
	v_pk_mul_f32 v[6:7], v[6:7], v[152:153]
	v_pk_mul_f32 v[2:3], v[2:3], v[148:149]
.LBB0_1384:
	v_exp_f32_e32 v98, v98
	v_exp_f32_e32 v99, v99
	v_exp_f32_e32 v100, v100
	v_exp_f32_e32 v101, v101
	v_exp_f32_e32 v147, v105
	v_add_f32_e32 v105, v98, v99
	v_exp_f32_e32 v102, v102
	v_exp_f32_e32 v103, v103
	v_exp_f32_e32 v104, v104
	v_cvt_pk_bf16_f32 v98, v98, v99
	v_add_f32_e32 v105, v100, v105
	v_cvt_pk_bf16_f32 v99, v100, v101
	v_add_f32_e32 v105, v101, v105
	v_cvt_pk_bf16_f32 v100, v102, v103
	v_cvt_pk_bf16_f32 v101, v104, v147
	v_add_f32_e32 v105, v102, v105
	v_exp_f32_e32 v106, v106
	v_exp_f32_e32 v107, v107
	s_waitcnt lgkmcnt(6)
	v_mfma_f32_32x32x16_bf16 v[2:17], v[98:101], v[126:129], v[2:17]
	v_add_f32_e32 v105, v103, v105
	v_exp_f32_e32 v108, v108
	v_add_f32_e32 v148, v104, v105
	v_cvt_pk_bf16_f32 v102, v106, v107
	v_add_f32_e32 v126, v147, v148
	v_exp_f32_e32 v109, v109
	v_add_f32_e32 v106, v106, v126
	v_exp_f32_e32 v110, v110
	v_add_f32_e32 v106, v107, v106
	v_exp_f32_e32 v111, v111
	v_add_f32_e32 v106, v108, v106
	v_exp_f32_e32 v112, v112
	v_exp_f32_e32 v113, v113
	v_add_f32_e32 v106, v109, v106
	s_waitcnt lgkmcnt(2)
	v_mfma_f32_32x32x16_bf16 v[18:33], v[98:101], v[118:121], v[18:33]
	v_add_f32_e32 v106, v110, v106
	v_cvt_pk_bf16_f32 v103, v108, v109
	v_add_f32_e32 v98, v111, v106
	v_cvt_pk_bf16_f32 v104, v110, v111
	v_cvt_pk_bf16_f32 v105, v112, v113
	s_nop 0
	v_add_f32_e32 v98, v112, v98
	v_mfma_f32_32x32x16_bf16 v[2:17], v[102:105], v[122:125], v[2:17]
	v_add_f32_e32 v98, v113, v98
	s_nop 0
	v_add_f32_e32 v98, v185, v98
	s_waitcnt lgkmcnt(0)
	v_mfma_f32_32x32x16_bf16 v[18:33], v[102:105], v[114:117], v[18:33]
	s_cbranch_execnz .LBB0_1345
	s_branch .LBB0_1386

.LBB0_1396:
	s_nop 1
	v_max_f32_e32 v50, v35, v35
	v_max_f32_e32 v51, v34, v34
	v_max_f32_e32 v50, v51, v50
	v_max3_f32 v51, v37, v38, v39
	v_max3_f32 v50, v50, v36, v40
	v_max3_f32 v51, v51, v42, v43
	v_max3_f32 v50, v50, v41, v44
	v_max3_f32 v51, v51, v46, v47
	v_max3_f32 v50, v50, v45, v48
	v_max3_f32 v50, v50, v49, v51
	v_mov_b32_e32 v51, v50
	s_nop 1
	v_permlane32_swap_b32_e32 v50, v51
	v_max_f32_e32 v51, v51, v51
	v_max_f32_e32 v50, v50, v50
	v_max_f32_e32 v50, v50, v51
	v_cmp_lt_f32_e32 vcc, s36, v50
	s_cbranch_vccz .LBB0_1400
	v_max_f32_e32 v50, v50, v50
	v_max_f32_e32 v50, 0, v50
	v_exp_f32_e64 v51, -v50
	v_add_f32_e32 v187, v187, v50
	v_xor_b32_e32 v66, 0x80000000, v187
	v_mov_b32_e32 v67, v66
	v_mov_b32_e32 v68, v66
	v_mov_b32_e32 v69, v66
	v_mov_b32_e32 v70, v66
	v_mov_b32_e32 v71, v66
	v_mov_b32_e32 v72, v66
	v_mov_b32_e32 v73, v66
	v_mov_b32_e32 v74, v66
	v_mov_b32_e32 v75, v66
	v_mov_b32_e32 v76, v66
	v_mov_b32_e32 v77, v66
	v_mov_b32_e32 v78, v66
	v_mov_b32_e32 v79, v66
	v_mov_b32_e32 v80, v66
	v_mov_b32_e32 v81, v66
	s_and_saveexec_b64 s[82:83], s[6:7]
	ds_write_b32 v202, v51 offset:40960
	s_or_b64 exec, exec, s[82:83]
	v_pk_add_f32 v[34:35], v[34:35], v[50:51] op_sel_hi:[1,0] neg_lo:[0,1] neg_hi:[0,1]
	v_pk_add_f32 v[36:37], v[36:37], v[50:51] op_sel_hi:[1,0] neg_lo:[0,1] neg_hi:[0,1]
	v_pk_add_f32 v[38:39], v[38:39], v[50:51] op_sel_hi:[1,0] neg_lo:[0,1] neg_hi:[0,1]
	v_pk_add_f32 v[40:41], v[40:41], v[50:51] op_sel_hi:[1,0] neg_lo:[0,1] neg_hi:[0,1]
	v_pk_add_f32 v[42:43], v[42:43], v[50:51] op_sel_hi:[1,0] neg_lo:[0,1] neg_hi:[0,1]
	v_pk_add_f32 v[44:45], v[44:45], v[50:51] op_sel_hi:[1,0] neg_lo:[0,1] neg_hi:[0,1]
	v_pk_add_f32 v[46:47], v[46:47], v[50:51] op_sel_hi:[1,0] neg_lo:[0,1] neg_hi:[0,1]
	v_pk_add_f32 v[48:49], v[48:49], v[50:51] op_sel_hi:[1,0] neg_lo:[0,1] neg_hi:[0,1]
	v_mul_f32_e32 v185, v185, v51
	ds_read_b128 v[50:53], v204 offset:40960
	ds_read_b128 v[54:57], v204 offset:40992
	ds_read_b128 v[58:61], v204 offset:41024
	ds_read_b128 v[62:65], v204 offset:41056
	s_waitcnt lgkmcnt(3)
	v_pk_mul_f32 v[20:21], v[20:21], v[52:53]
	s_waitcnt lgkmcnt(2)
	v_pk_mul_f32 v[24:25], v[24:25], v[56:57]
	s_waitcnt lgkmcnt(1)
	v_pk_mul_f32 v[28:29], v[28:29], v[60:61]
	s_waitcnt lgkmcnt(0)
	v_pk_mul_f32 v[32:33], v[32:33], v[64:65]
	v_pk_mul_f32 v[16:17], v[16:17], v[64:65]
	v_pk_mul_f32 v[12:13], v[12:13], v[60:61]
	v_pk_mul_f32 v[8:9], v[8:9], v[56:57]
	v_pk_mul_f32 v[4:5], v[4:5], v[52:53]
	v_pk_mul_f32 v[30:31], v[30:31], v[62:63]
	v_pk_mul_f32 v[26:27], v[26:27], v[58:59]
	v_pk_mul_f32 v[22:23], v[22:23], v[54:55]
	v_pk_mul_f32 v[18:19], v[18:19], v[50:51]
	v_pk_mul_f32 v[14:15], v[14:15], v[62:63]
	v_pk_mul_f32 v[10:11], v[10:11], v[58:59]
	v_pk_mul_f32 v[6:7], v[6:7], v[54:55]
	v_pk_mul_f32 v[2:3], v[2:3], v[50:51]
	s_branch .LBB0_1401
.LBB0_1400:
.LBB0_1401:
	v_exp_f32_e32 v34, v34
	v_exp_f32_e32 v35, v35
	v_exp_f32_e32 v36, v36
	v_exp_f32_e32 v37, v37
	v_exp_f32_e32 v50, v41
	v_add_f32_e32 v41, v34, v35
	v_exp_f32_e32 v38, v38
	v_exp_f32_e32 v39, v39
	v_exp_f32_e32 v40, v40
	v_cvt_pk_bf16_f32 v34, v34, v35
	v_add_f32_e32 v41, v36, v41
	v_cvt_pk_bf16_f32 v35, v36, v37
	v_add_f32_e32 v41, v37, v41
	v_cvt_pk_bf16_f32 v36, v38, v39
	v_cvt_pk_bf16_f32 v37, v40, v50
	v_add_f32_e32 v41, v38, v41
	v_exp_f32_e32 v42, v42
	v_exp_f32_e32 v43, v43
	v_exp_f32_e32 v44, v44
	v_add_f32_e32 v41, v39, v41
	v_exp_f32_e32 v45, v45
	v_exp_f32_e32 v46, v46
	v_exp_f32_e32 v47, v47
	v_exp_f32_e32 v48, v48
	v_exp_f32_e32 v49, v49
	s_waitcnt lgkmcnt(2)
	v_mfma_f32_32x32x16_bf16 v[18:33], v[34:37], v[102:105], v[18:33]
	v_add_f32_e32 v51, v40, v41
	v_cvt_pk_bf16_f32 v38, v42, v43
	v_add_f32_e32 v50, v50, v51
	v_cvt_pk_bf16_f32 v39, v44, v45
	v_add_f32_e32 v42, v42, v50
	v_mfma_f32_32x32x16_bf16 v[2:17], v[34:37], v[110:113], v[2:17]
	v_cvt_pk_bf16_f32 v40, v46, v47
	v_cvt_pk_bf16_f32 v41, v48, v49
	v_add_f32_e32 v42, v43, v42
	s_nop 0
	v_add_f32_e32 v42, v44, v42
	s_waitcnt lgkmcnt(0)
	v_mfma_f32_32x32x16_bf16 v[18:33], v[38:41], v[98:101], v[18:33]
	v_add_f32_e32 v42, v45, v42
	s_nop 0
	v_add_f32_e32 v42, v46, v42
	s_nop 0
	v_add_f32_e32 v34, v47, v42
	v_mfma_f32_32x32x16_bf16 v[2:17], v[38:41], v[106:109], v[2:17]
	s_nop 0
	v_add_f32_e32 v34, v48, v34
	s_nop 0
	v_add_f32_e32 v34, v49, v34
	s_nop 0
	v_add_f32_e32 v98, v185, v34
	s_cmp_ge_i32 s67, s39
	s_cselect_b64 s[82:83], -1, 0
	s_and_b64 vcc, exec, s[82:83]
	s_cbranch_vccz .LBB0_1346
	s_branch .LBB0_1347
